# plus: sc1 write-through on the layer-ahead weight-conversion stores
# speedup vs baseline: 1.0247x; 1.0100x over previous
; #define LAS __attribute__((address_space(3)))
; #define GAS __attribute__((address_space(1)))
; __device__ __forceinline__ unsigned pk2(float lo, float hi) { unsigned r; asm("v_cvt_pk_bf16_f32 %0, %1, %2" : "=v"(r) : "v"(lo), "v"(hi)); return r; }
; __device__ __forceinline__ void item_store(const ItemP& p, const f32x4 (&v)[16], LAS float* scr, int lane) {
;     ...
;     for (int i = 0; i < 16; ++i) { LAS float* d = scr + (4 * i + (lane >> 4)) * 65 + c4; d[0] = v[i].x; d[1] = v[i].y; d[2] = v[i].z; d[3] = v[i].w; }
;     asm volatile("s_waitcnt lgkmcnt(0)" ::: "memory");
;     const int c = lane & 7;
; #pragma unroll
;     for (int j = 0; j < 8; ++j) {
;         const int n = 8 * j + (lane >> 3);
;         const LAS float* s = scr + (8 * c) * 65 + n;
;         u32x4 o; o.x = pk2(s[0], s[65]); o.y = pk2(s[2 * 65], s[3 * 65]); o.z = pk2(s[4 * 65], s[5 * 65]); o.w = pk2(s[6 * 65], s[7 * 65]);
;         *(GAS u32x4*)(p.dst + (size_t)n * DM + 8 * c) = o;
;     }
;     asm volatile("s_waitcnt lgkmcnt(0)" ::: "memory");
.LBB0_450:
	v_add_u32_e32 v177, 0x1458, v170
	s_waitcnt vmcnt(0)
	ds_write2_b32 v170, v4, v5 offset1:1
	ds_write2_b32 v170, v6, v7 offset0:2 offset1:3
	ds_write2_b32 v177, v26, v27 offset1:1
	v_add_u32_e32 v26, 0x1860, v170
	ds_write2_b32 v26, v28, v29 offset1:1
	v_add_u32_e32 v27, 0x1868, v170
	v_add_u32_e32 v28, 0x1c70, v170
	v_add_u32_e32 v29, 0x1c78, v170
	ds_write2_b32 v27, v30, v31 offset1:1
	ds_write2_b32 v28, v32, v33 offset1:1
	ds_write2_b32 v29, v34, v35 offset1:1
	v_add_u32_e32 v30, 0x2080, v170
	v_add_u32_e32 v31, 0x2088, v170
	v_add_u32_e32 v32, 0x2490, v170
	v_add_u32_e32 v33, 0x2498, v170
	v_add_u32_e32 v34, 0x28a0, v170
	v_add_u32_e32 v0, 0x410, v170
	v_add_u32_e32 v154, 0x418, v170
	v_add_u32_e32 v155, 0x820, v170
	v_add_u32_e32 v171, 0x828, v170
	v_add_u32_e32 v172, 0xc30, v170
	v_add_u32_e32 v173, 0xc38, v170
	v_add_u32_e32 v174, 0x1040, v170
	v_add_u32_e32 v175, 0x1048, v170
	v_add_u32_e32 v176, 0x1450, v170
	ds_write2_b32 v30, v36, v37 offset1:1
	ds_write2_b32 v31, v38, v39 offset1:1
	ds_write2_b32 v32, v40, v41 offset1:1
	ds_write2_b32 v33, v42, v43 offset1:1
	ds_write2_b32 v34, v44, v45 offset1:1
	v_add_u32_e32 v35, 0x28a8, v170
	v_add_u32_e32 v36, 0x2cb0, v170
	v_add_u32_e32 v37, 0x2cb8, v170
	v_add_u32_e32 v38, 0x30c0, v170
	v_add_u32_e32 v39, 0x30c8, v170
	v_add_u32_e32 v40, 0x34d0, v170
	v_add_u32_e32 v41, 0x34d8, v170
	v_add_u32_e32 v42, 0x38e0, v170
	v_add_u32_e32 v43, 0x38e8, v170
	v_add_u32_e32 v44, 0x3cf0, v170
	v_add_u32_e32 v45, 0x3cf8, v170
	ds_write2_b32 v0, v8, v9 offset1:1
	ds_write2_b32 v154, v10, v11 offset1:1
	ds_write2_b32 v155, v12, v13 offset1:1
	ds_write2_b32 v171, v14, v15 offset1:1
	ds_write2_b32 v172, v16, v17 offset1:1
	ds_write2_b32 v173, v18, v19 offset1:1
	ds_write2_b32 v174, v20, v21 offset1:1
	ds_write2_b32 v175, v22, v23 offset1:1
	ds_write2_b32 v176, v24, v25 offset1:1
	ds_write2_b32 v35, v46, v47 offset1:1
	ds_write2_b32 v36, v48, v49 offset1:1
	ds_write2_b32 v37, v50, v51 offset1:1
	ds_write2_b32 v38, v52, v53 offset1:1
	ds_write2_b32 v39, v54, v55 offset1:1
	ds_write2_b32 v40, v56, v57 offset1:1
	ds_write2_b32 v41, v58, v59 offset1:1
	ds_write2_b32 v42, v60, v61 offset1:1
	ds_write2_b32 v43, v62, v63 offset1:1
	ds_write2_b32 v44, v64, v65 offset1:1
	ds_write2_b32 v45, v66, v67 offset1:1
	s_waitcnt lgkmcnt(0)
	v_add_u32_e32 v46, 0x400, v169
	ds_read2_b32 v[6:7], v169 offset0:65 offset1:73
	ds_read2_b32 v[8:9], v169 offset1:8
	ds_read2_b32 v[10:11], v169 offset0:130 offset1:138
	ds_read2_b32 v[12:13], v169 offset0:195 offset1:203
	ds_read2_b32 v[14:15], v46 offset0:4 offset1:12
	ds_read2_b32 v[16:17], v46 offset0:69 offset1:77
	ds_read2_b32 v[18:19], v46 offset0:134 offset1:142
	ds_read2_b32 v[20:21], v46 offset0:199 offset1:207
	v_mov_b32_e32 v137, v1
	v_lshl_add_u64 v[22:23], s[6:7], 0, v[136:137]
	v_mov_b32_e32 v139, v1
	v_lshl_add_u64 v[24:25], v[22:23], 0, v[138:139]
	s_waitcnt lgkmcnt(6)
	v_cvt_pk_bf16_f32 v2, v8, v6
	s_waitcnt lgkmcnt(4)
	v_cvt_pk_bf16_f32 v3, v10, v12
	s_waitcnt lgkmcnt(2)
	v_cvt_pk_bf16_f32 v4, v14, v16
	s_waitcnt lgkmcnt(0)
	v_cvt_pk_bf16_f32 v5, v18, v20
	global_store_dwordx4 v[24:25], v[2:5], off sc1
	v_mov_b32_e32 v141, v1
	v_mov_b32_e32 v143, v1
	v_cvt_pk_bf16_f32 v2, v9, v7
	v_cvt_pk_bf16_f32 v3, v11, v13
	v_cvt_pk_bf16_f32 v4, v15, v17
	v_cvt_pk_bf16_f32 v5, v19, v21
	ds_read2_b32 v[8:9], v169 offset0:16 offset1:24
	ds_read2_b32 v[10:11], v169 offset0:81 offset1:89
	ds_read2_b32 v[12:13], v169 offset0:146 offset1:154
	ds_read2_b32 v[14:15], v169 offset0:211 offset1:219
	ds_read2_b32 v[16:17], v46 offset0:20 offset1:28
	ds_read2_b32 v[18:19], v46 offset0:85 offset1:93
	ds_read2_b32 v[20:21], v46 offset0:150 offset1:158
	ds_read2_b32 v[24:25], v46 offset0:215 offset1:223
	v_lshl_add_u64 v[6:7], v[22:23], 0, v[140:141]
	global_store_dwordx4 v[6:7], v[2:5], off sc1
	v_lshl_add_u64 v[6:7], v[22:23], 0, v[142:143]
	v_mov_b32_e32 v145, v1
	s_waitcnt lgkmcnt(6)
	v_cvt_pk_bf16_f32 v2, v8, v10
	s_waitcnt lgkmcnt(4)
	v_cvt_pk_bf16_f32 v3, v12, v14
	s_waitcnt lgkmcnt(2)
	v_cvt_pk_bf16_f32 v4, v16, v18
	s_waitcnt lgkmcnt(0)
	v_cvt_pk_bf16_f32 v5, v20, v24
	global_store_dwordx4 v[6:7], v[2:5], off sc1
	v_lshl_add_u64 v[6:7], v[22:23], 0, v[144:145]
	v_mov_b32_e32 v147, v1
	v_cvt_pk_bf16_f32 v2, v9, v11
	v_cvt_pk_bf16_f32 v3, v13, v15
	v_cvt_pk_bf16_f32 v4, v17, v19
	v_cvt_pk_bf16_f32 v5, v21, v25
	ds_read2_b32 v[8:9], v169 offset0:32 offset1:40
	ds_read2_b32 v[10:11], v169 offset0:97 offset1:105
	ds_read2_b32 v[12:13], v169 offset0:162 offset1:170
	ds_read2_b32 v[14:15], v169 offset0:227 offset1:235
	ds_read2_b32 v[16:17], v46 offset0:36 offset1:44
	ds_read2_b32 v[18:19], v46 offset0:101 offset1:109
	ds_read2_b32 v[20:21], v46 offset0:166 offset1:174
	ds_read2_b32 v[24:25], v46 offset0:231 offset1:239
	global_store_dwordx4 v[6:7], v[2:5], off sc1
	v_lshl_add_u64 v[6:7], v[22:23], 0, v[146:147]
	v_mov_b32_e32 v149, v1
	s_waitcnt lgkmcnt(6)
	v_cvt_pk_bf16_f32 v2, v8, v10
	s_waitcnt lgkmcnt(4)
	v_cvt_pk_bf16_f32 v3, v12, v14
	s_waitcnt lgkmcnt(2)
	v_cvt_pk_bf16_f32 v4, v16, v18
	s_waitcnt lgkmcnt(0)
	v_cvt_pk_bf16_f32 v5, v20, v24
	global_store_dwordx4 v[6:7], v[2:5], off sc1
	v_lshl_add_u64 v[6:7], v[22:23], 0, v[148:149]
	v_mov_b32_e32 v151, v1
	v_cvt_pk_bf16_f32 v2, v9, v11
	v_cvt_pk_bf16_f32 v3, v13, v15
	v_cvt_pk_bf16_f32 v4, v17, v19
	v_cvt_pk_bf16_f32 v5, v21, v25
	ds_read2_b32 v[8:9], v169 offset0:48 offset1:56
	ds_read2_b32 v[10:11], v169 offset0:113 offset1:121
	ds_read2_b32 v[12:13], v169 offset0:178 offset1:186
	ds_read2_b32 v[14:15], v169 offset0:243 offset1:251
	ds_read2_b32 v[16:17], v46 offset0:52 offset1:60
	ds_read2_b32 v[18:19], v46 offset0:117 offset1:125
	ds_read2_b32 v[20:21], v46 offset0:182 offset1:190
	ds_read2_b32 v[24:25], v46 offset0:247 offset1:255
	global_store_dwordx4 v[6:7], v[2:5], off sc1
	v_lshl_add_u64 v[6:7], v[22:23], 0, v[150:151]
	v_mov_b32_e32 v153, v1
	s_waitcnt lgkmcnt(6)
; #define LAS __attribute__((address_space(3)))
; #define GAS __attribute__((address_space(1)))
; __device__ __forceinline__ unsigned pk2(float lo, float hi) { unsigned r; asm("v_cvt_pk_bf16_f32 %0, %1, %2" : "=v"(r) : "v"(lo), "v"(hi)); return r; }
; __device__ __forceinline__ void item_store(const ItemP& p, const f32x4 (&v)[16], LAS float* scr, int lane) {
;     ...
;     for (int i = 0; i < 16; ++i) { LAS float* d = scr + (4 * i + (lane >> 4)) * 65 + c4; d[0] = v[i].x; d[1] = v[i].y; d[2] = v[i].z; d[3] = v[i].w; }
;     asm volatile("s_waitcnt lgkmcnt(0)" ::: "memory");
;     const int c = lane & 7;
; #pragma unroll
;     for (int j = 0; j < 8; ++j) {
;         const int n = 8 * j + (lane >> 3);
;         const LAS float* s = scr + (8 * c) * 65 + n;
;         u32x4 o; o.x = pk2(s[0], s[65]); o.y = pk2(s[2 * 65], s[3 * 65]); o.z = pk2(s[4 * 65], s[5 * 65]); o.w = pk2(s[6 * 65], s[7 * 65]);
;         *(GAS u32x4*)(p.dst + (size_t)n * DM + 8 * c) = o;
;     }
;     asm volatile("s_waitcnt lgkmcnt(0)" ::: "memory");
	v_cvt_pk_bf16_f32 v2, v8, v10
	s_waitcnt lgkmcnt(4)
	v_cvt_pk_bf16_f32 v3, v12, v14
	s_waitcnt lgkmcnt(2)
	v_cvt_pk_bf16_f32 v4, v16, v18
	s_waitcnt lgkmcnt(0)
	v_cvt_pk_bf16_f32 v5, v20, v24
	global_store_dwordx4 v[6:7], v[2:5], off sc1
	v_lshl_add_u64 v[6:7], v[22:23], 0, v[152:153]
	v_lshl_add_u64 v[22:23], s[2:3], 0, v[136:137]
	v_cvt_pk_bf16_f32 v2, v9, v11
	v_cvt_pk_bf16_f32 v3, v13, v15
	v_cvt_pk_bf16_f32 v4, v17, v19
	v_cvt_pk_bf16_f32 v5, v21, v25
	global_store_dwordx4 v[6:7], v[2:5], off sc1
	s_waitcnt lgkmcnt(0)
	ds_write2_b32 v170, v68, v69 offset1:1
	ds_write2_b32 v170, v70, v71 offset0:2 offset1:3
	ds_write2_b32 v0, v72, v73 offset1:1
	ds_write2_b32 v154, v74, v75 offset1:1
	ds_write2_b32 v155, v76, v77 offset1:1
	ds_write2_b32 v171, v78, v79 offset1:1
	ds_write2_b32 v172, v80, v81 offset1:1
	ds_write2_b32 v173, v82, v83 offset1:1
	ds_write2_b32 v174, v84, v85 offset1:1
	ds_write2_b32 v175, v86, v87 offset1:1
	ds_write2_b32 v176, v88, v89 offset1:1
	ds_write2_b32 v177, v90, v91 offset1:1
	ds_write2_b32 v26, v92, v93 offset1:1
	ds_write2_b32 v27, v94, v95 offset1:1
	ds_write2_b32 v28, v96, v97 offset1:1
	ds_write2_b32 v29, v98, v99 offset1:1
	ds_write2_b32 v30, v100, v101 offset1:1
	ds_write2_b32 v31, v102, v103 offset1:1
	ds_write2_b32 v32, v104, v105 offset1:1
	ds_write2_b32 v33, v106, v107 offset1:1
	ds_write2_b32 v34, v108, v109 offset1:1
	ds_write2_b32 v35, v110, v111 offset1:1
	ds_write2_b32 v36, v112, v113 offset1:1
	ds_write2_b32 v37, v114, v115 offset1:1
	ds_write2_b32 v38, v116, v117 offset1:1
	ds_write2_b32 v39, v118, v119 offset1:1
	ds_write2_b32 v40, v120, v121 offset1:1
	ds_write2_b32 v41, v122, v123 offset1:1
	ds_write2_b32 v42, v124, v125 offset1:1
	ds_write2_b32 v43, v126, v127 offset1:1
	ds_write2_b32 v44, v128, v129 offset1:1
	ds_write2_b32 v45, v130, v131 offset1:1
	s_waitcnt lgkmcnt(0)
	ds_read2_b32 v[6:7], v169 offset0:65 offset1:73
	ds_read2_b32 v[8:9], v169 offset1:8
	ds_read2_b32 v[10:11], v169 offset0:130 offset1:138
	ds_read2_b32 v[12:13], v169 offset0:195 offset1:203
	ds_read2_b32 v[14:15], v46 offset0:4 offset1:12
	ds_read2_b32 v[16:17], v46 offset0:69 offset1:77
	ds_read2_b32 v[18:19], v46 offset0:134 offset1:142
	ds_read2_b32 v[20:21], v46 offset0:199 offset1:207
	v_lshl_add_u64 v[24:25], v[22:23], 0, v[138:139]
	s_waitcnt lgkmcnt(6)
	v_cvt_pk_bf16_f32 v2, v8, v6
	s_waitcnt lgkmcnt(4)
	v_cvt_pk_bf16_f32 v3, v10, v12
	s_waitcnt lgkmcnt(2)
	v_cvt_pk_bf16_f32 v4, v14, v16
	s_waitcnt lgkmcnt(0)
	v_cvt_pk_bf16_f32 v5, v18, v20
	global_store_dwordx4 v[24:25], v[2:5], off sc1
	s_mov_b64 s[2:3], 0
	s_nop 0
	v_cvt_pk_bf16_f32 v2, v9, v7
	v_cvt_pk_bf16_f32 v3, v11, v13
	v_cvt_pk_bf16_f32 v4, v15, v17
	v_cvt_pk_bf16_f32 v5, v19, v21
	ds_read2_b32 v[8:9], v169 offset0:16 offset1:24
	ds_read2_b32 v[10:11], v169 offset0:81 offset1:89
	ds_read2_b32 v[12:13], v169 offset0:146 offset1:154
	ds_read2_b32 v[14:15], v169 offset0:211 offset1:219
	ds_read2_b32 v[16:17], v46 offset0:20 offset1:28
	ds_read2_b32 v[18:19], v46 offset0:85 offset1:93
	ds_read2_b32 v[20:21], v46 offset0:150 offset1:158
	ds_read2_b32 v[24:25], v46 offset0:215 offset1:223
	v_lshl_add_u64 v[6:7], v[22:23], 0, v[140:141]
	global_store_dwordx4 v[6:7], v[2:5], off sc1
	v_lshl_add_u64 v[6:7], v[22:23], 0, v[142:143]
	s_waitcnt lgkmcnt(6)
	v_cvt_pk_bf16_f32 v2, v8, v10
	s_waitcnt lgkmcnt(4)
	v_cvt_pk_bf16_f32 v3, v12, v14
	s_waitcnt lgkmcnt(2)
	v_cvt_pk_bf16_f32 v4, v16, v18
	s_waitcnt lgkmcnt(0)
	v_cvt_pk_bf16_f32 v5, v20, v24
	global_store_dwordx4 v[6:7], v[2:5], off sc1
	v_lshl_add_u64 v[6:7], v[22:23], 0, v[144:145]
	s_nop 0
	v_cvt_pk_bf16_f32 v2, v9, v11
	v_cvt_pk_bf16_f32 v3, v13, v15
	v_cvt_pk_bf16_f32 v4, v17, v19
	v_cvt_pk_bf16_f32 v5, v21, v25
	ds_read2_b32 v[8:9], v169 offset0:32 offset1:40
	ds_read2_b32 v[10:11], v169 offset0:97 offset1:105
	ds_read2_b32 v[12:13], v169 offset0:162 offset1:170
	ds_read2_b32 v[14:15], v169 offset0:227 offset1:235
	ds_read2_b32 v[16:17], v46 offset0:36 offset1:44
	ds_read2_b32 v[18:19], v46 offset0:101 offset1:109
	ds_read2_b32 v[20:21], v46 offset0:166 offset1:174
	ds_read2_b32 v[24:25], v46 offset0:231 offset1:239
	global_store_dwordx4 v[6:7], v[2:5], off sc1
	v_lshl_add_u64 v[6:7], v[22:23], 0, v[146:147]
	s_waitcnt lgkmcnt(6)
	v_cvt_pk_bf16_f32 v2, v8, v10
	s_waitcnt lgkmcnt(4)
	v_cvt_pk_bf16_f32 v3, v12, v14
	s_waitcnt lgkmcnt(2)
	v_cvt_pk_bf16_f32 v4, v16, v18
	s_waitcnt lgkmcnt(0)
	v_cvt_pk_bf16_f32 v5, v20, v24
	global_store_dwordx4 v[6:7], v[2:5], off sc1
	v_lshl_add_u64 v[6:7], v[22:23], 0, v[148:149]
	s_nop 0
	v_cvt_pk_bf16_f32 v2, v9, v11
	v_cvt_pk_bf16_f32 v3, v13, v15
	v_cvt_pk_bf16_f32 v4, v17, v19
	v_cvt_pk_bf16_f32 v5, v21, v25
	ds_read2_b32 v[8:9], v169 offset0:48 offset1:56
	ds_read2_b32 v[10:11], v169 offset0:113 offset1:121
	ds_read2_b32 v[12:13], v169 offset0:178 offset1:186
	ds_read2_b32 v[14:15], v169 offset0:243 offset1:251
	ds_read2_b32 v[16:17], v46 offset0:52 offset1:60
	ds_read2_b32 v[18:19], v46 offset0:117 offset1:125
	ds_read2_b32 v[20:21], v46 offset0:182 offset1:190
	ds_read2_b32 v[24:25], v46 offset0:247 offset1:255
	global_store_dwordx4 v[6:7], v[2:5], off sc1
	v_lshl_add_u64 v[6:7], v[22:23], 0, v[150:151]
	s_waitcnt lgkmcnt(6)
	v_cvt_pk_bf16_f32 v2, v8, v10
	s_waitcnt lgkmcnt(4)
	v_cvt_pk_bf16_f32 v3, v12, v14
	s_waitcnt lgkmcnt(2)
	v_cvt_pk_bf16_f32 v4, v16, v18
	s_waitcnt lgkmcnt(0)
	v_cvt_pk_bf16_f32 v5, v20, v24
	global_store_dwordx4 v[6:7], v[2:5], off sc1
	v_lshl_add_u64 v[6:7], v[22:23], 0, v[152:153]
	s_nop 0
	v_cvt_pk_bf16_f32 v2, v9, v11
	v_cvt_pk_bf16_f32 v3, v13, v15
	v_cvt_pk_bf16_f32 v4, v17, v19
	v_cvt_pk_bf16_f32 v5, v21, v25
	global_store_dwordx4 v[6:7], v[2:5], off sc1
	s_waitcnt lgkmcnt(0)
